# attention items: window mask folded into a -inf padded bias table in the LDS tail; per key tile 32 plain LDS reads + 32 v_fmamk, K fragments of each 16-key group read in one batch
# speedup vs baseline: 1.0136x; 1.0073x over previous
; #define LAS __attribute__((address_space(3)))
; __device__ __forceinline__ unsigned xb_xcc_id() { return (unsigned)__builtin_amdgcn_s_getreg((3 << 11) | 20) & 0xFu; }
; __global__ void __launch_bounds__(NTHR) fwd_megakernel(const Params P) {
;   cg::grid_group grid = cg::this_grid();
;   __shared__ uint4 xb_words;
;   __shared__ int s_vb[4];
;   const int wvi = __builtin_amdgcn_readfirstlane((int)(threadIdx.x >> 6));
;   if (threadIdx.x == 0) xb_words = make_uint4(0u, 0u, 0u, 0u);
;   __syncthreads();
;   (void)xcd_barrier_post((unsigned*)(wsp_plain(P) + OFF_CTL + 65536), (volatile LAS unsigned*)&xb_words, wvi);
;   if (threadIdx.x == 0) {
;     const unsigned x = xb_xcc_id() & 7u;
;     s_vb[1] = (int)x;
;     s_vb[2] = (int)atomicAdd((unsigned*)(P.ws + OFF_CTL + 8192) + x, 1u);
;   }
;   phase0(P, wvi);
;   if (P.ws == nullptr) grid.sync();
;   xcd_barrier(P, (volatile LAS unsigned*)&xb_words, wvi);
;   if (threadIdx.x == 0) {
;     bool even = (gridDim.x & 7u) == 0u;
;     for (int j = 0; j < 8; ++j)
;       even = even && (__hip_atomic_load((unsigned*)(P.ws + OFF_CTL + 8192) + j, __ATOMIC_RELAXED, __HIP_MEMORY_SCOPE_AGENT) == gridDim.x / 8u);
;     s_vb[0] = even ? (s_vb[1] + 8 * s_vb[2]) : (int)blockIdx.x;
;   }
;   __syncthreads();
.LBB0_116:
	s_or_b64 exec, exec, s[0:1]
	s_waitcnt lgkmcnt(0)
	s_add_u32 s52, s50, 0x22700000
	s_addc_u32 s53, s51, 0
	s_lshl_b32 s1, s41, 3
	s_lshl_b32 s31, s42, 3
	v_writelane_b32 v246, s1, 6
	s_add_u32 s1, s50, 0x3df10000
	s_mul_i32 s0, s43, s42
	v_writelane_b32 v246, s1, 7
	s_addc_u32 s1, s51, 0
	v_writelane_b32 v246, s1, 8
	s_mul_i32 s0, s0, s38
	v_writelane_b32 v246, s0, 9
	s_add_u32 s0, s50, 0x3df10200
	s_addc_u32 s1, s51, 0
	v_writelane_b32 v246, s0, 10
	v_mbcnt_lo_u32_b32 v0, -1, 0
	v_mbcnt_hi_u32_b32 v0, -1, v0
	v_add_u32_e32 v0, s48, v0
	v_readlane_b32 s2, v246, 0
	v_readlane_b32 s3, v246, 1
	s_nop 4
	s_load_dwordx2 s[4:5], s[2:3], 0x58
	v_min_u32_e32 v1, 0x100, v0
	global_load_ubyte v255, v1, s[2:3] offset:168
	v_lshlrev_b32_e32 v2, 2, v0
	s_waitcnt lgkmcnt(0)
	global_load_dword v4, v2, s[4:5]
	v_add_u32_e32 v2, 0x23820, v2
	s_waitcnt vmcnt(0)
	ds_write_b32 v2, v4
	v_mov_b32_e32 v5, 0xff800000
	ds_write_b32 v2, v5 offset:2048
	s_waitcnt lgkmcnt(0)
	s_barrier
	s_nop 0
	v_writelane_b32 v246, s1, 11
	s_add_u32 s0, s50, 0x3df10400
	s_addc_u32 s1, s51, 0
	v_writelane_b32 v246, s0, 12
	v_mov_b32_e32 v145, 0
	s_nop 0
	v_writelane_b32 v246, s1, 13
	s_add_u32 s0, s50, 0x3df10500
	s_addc_u32 s1, s51, 0
	v_writelane_b32 v246, s0, 14
	v_mov_b32_e32 v165, 0x358637bd
	v_mov_b32_e32 v167, 0x1000
	v_writelane_b32 v246, s1, 15
	s_add_u32 s0, s50, 0x3df10600
	s_addc_u32 s1, s51, 0
	v_writelane_b32 v246, s0, 16
	v_mov_b32_e32 v196, 0x2000
	v_mov_b32_e32 v197, 1
	v_writelane_b32 v246, s1, 17
	s_add_u32 s0, s50, 0x3df10700
	s_addc_u32 s1, s51, 0
	v_writelane_b32 v246, s0, 18
	v_mov_b32_e32 v198, 0x3ecc95a3
	v_bfrev_b32_e32 v199, 0.5
	v_writelane_b32 v246, s1, 19
	s_add_u32 s0, s50, 0x3df10800
	s_addc_u32 s1, s51, 0
	v_writelane_b32 v246, s0, 20
	v_mov_b32_e32 v200, 0x7f800000
	v_mov_b32_e32 v201, 0x7fc00000
	v_writelane_b32 v246, s1, 21
	s_add_u32 s0, s50, 0x3df10900
	s_addc_u32 s1, s51, 0
	v_writelane_b32 v246, s0, 22
	v_mov_b32_e32 v202, 0xff800000
	v_mov_b32_e32 v203, 0x3e800000
	v_writelane_b32 v246, s1, 23
	s_add_u32 s0, s50, 0x3df10a00
	s_addc_u32 s1, s51, 0
	v_writelane_b32 v246, s0, 24
	v_mov_b32_e32 v204, 0x3e000000
	v_mov_b32_e32 v205, 0x35700000
	v_writelane_b32 v246, s1, 25
	s_add_u32 s0, s50, 0x3df10b00
	s_addc_u32 s1, s51, 0
	v_writelane_b32 v246, s0, 26
	v_mov_b32_e32 v206, 0x34f00000
	v_mov_b32_e32 v207, 0x3300
	v_writelane_b32 v246, s1, 27
	s_add_u32 s0, s50, 0x3df10c00
	s_addc_u32 s1, s51, 0
	v_writelane_b32 v246, s0, 28
	v_mov_b32_e32 v208, 0x3000
	v_mov_b32_e32 v209, 0x2c00
	v_writelane_b32 v246, s1, 29
	s_add_u32 s0, s50, 0x3df10d00
	s_addc_u32 s1, s51, 0
	v_writelane_b32 v246, s0, 30
	s_movk_i32 s85, 0x3000
	s_mov_b32 s88, 0x800000
	v_writelane_b32 v246, s1, 31
	s_add_u32 s0, s50, 0x3df10e00
	s_addc_u32 s1, s51, 0
	v_writelane_b32 v246, s0, 32
	s_movk_i32 s89, 0x2000
	s_movk_i32 s90, 0xd000
	v_writelane_b32 v246, s1, 33
	s_add_u32 s0, s50, 0x3df10f00
	s_addc_u32 s1, s51, 0
	v_writelane_b32 v246, s0, 34
	s_movk_i32 s91, 0x1800
	s_mov_b32 s93, 0x32700000
	v_writelane_b32 v246, s1, 35
	s_add_u32 s0, s50, 0x3df11000
	s_addc_u32 s1, s51, 0
	v_writelane_b32 v246, s0, 36
	s_mov_b32 s96, 0x26700000
	s_movk_i32 s97, 0x101
	v_writelane_b32 v246, s1, 37
	s_add_u32 s0, s50, 0x3df11100
	s_addc_u32 s1, s51, 0
	v_writelane_b32 v246, s0, 38
	s_mov_b32 s19, 0
	s_mov_b64 s[86:87], 0x40000
	v_writelane_b32 v246, s1, 39
	s_add_u32 s0, s50, 0x3df11200
	s_addc_u32 s1, s51, 0
	v_writelane_b32 v246, s0, 40
	s_mov_b64 s[46:47], 0x100
	s_nop 0
	v_writelane_b32 v246, s1, 41
	s_add_u32 s0, s50, 0x3df11300
	s_addc_u32 s1, s51, 0
	v_writelane_b32 v246, s0, 42
	s_nop 1
	v_writelane_b32 v246, s1, 43
	s_add_u32 s0, s50, 0x3df13400
	s_addc_u32 s1, s51, 0
	v_writelane_b32 v246, s0, 44
	s_nop 1
	v_writelane_b32 v246, s1, 45
	s_add_u32 s0, s50, 0x3df13500
	s_addc_u32 s1, s51, 0
	v_writelane_b32 v246, s0, 46
	s_lshr_b32 s5, s33, 8
	s_nop 0
	v_writelane_b32 v246, s1, 47
	s_lshl_b32 s0, s39, 10
	v_writelane_b32 v246, s0, 48
	s_and_b32 s0, s33, 0xffffff00
	s_cmpk_eq_i32 s0, 0x100
	s_cselect_b64 s[0:1], -1, 0
	s_lshl_b32 s8, s39, 4
	v_writelane_b32 v246, s0, 49
	s_and_b32 s3, s8, 0x3fffffc0
	s_or_b32 s2, s3, 16
	v_writelane_b32 v246, s1, 50
	v_writelane_b32 v246, s2, 51
	s_lshl_b32 s1, s3, 7
	v_writelane_b32 v246, s3, 52
	s_or_b32 s3, s3, 32
	s_lshl_b32 s0, s39, 12
	v_writelane_b32 v246, s3, 53
	s_or_b32 s4, s8, 48
	s_lshl_b32 s6, s39, 5
	s_and_b32 s0, s0, 0x3000
	s_lshl_b32 s2, s2, 7
	s_lshl_b32 s3, s3, 7
	v_writelane_b32 v246, s4, 54
	s_lshl_b32 s4, s4, 7
	s_lshl_b32 s49, s5, 6
	s_and_b32 s54, s6, 0x60
	s_cmp_eq_u32 s5, 1
	s_cselect_b64 s[56:57], -1, 0
	s_add_u32 s34, s50, 0xa700000
	s_addc_u32 s35, s51, 0
	v_writelane_b32 v246, s6, 55
	s_add_u32 s6, s50, 0x16700000
	s_addc_u32 s7, s51, 0
	v_writelane_b32 v246, s6, 56
	s_lshl_b32 s18, s42, 9
	v_writelane_b32 v243, s56, 0
	v_writelane_b32 v246, s7, 57
	s_add_u32 s6, s50, 0x34700000
	s_addc_u32 s7, s51, 0
	v_writelane_b32 v246, s6, 58
	v_writelane_b32 v243, s57, 1
	v_writelane_b32 v243, s34, 2
	v_writelane_b32 v246, s7, 59
	s_add_u32 s6, s50, 0x34f00000
	s_addc_u32 s7, s51, 0
	v_writelane_b32 v246, s6, 60
	v_writelane_b32 v243, s35, 3
	v_writelane_b32 v243, s18, 4
	v_writelane_b32 v246, s7, 61
	s_add_u32 s6, s50, 0x35700000
	s_addc_u32 s7, s51, 0
	v_writelane_b32 v246, s6, 62
	s_nop 1
	v_writelane_b32 v246, s7, 63
	s_add_u32 s6, s50, 0x3e000000
	s_addc_u32 s7, s51, 0
	v_writelane_b32 v245, s6, 0
	s_nop 1
	v_writelane_b32 v245, s7, 1
	s_add_u32 s6, s50, 0x3e800000
	s_addc_u32 s7, s51, 0
	v_writelane_b32 v245, s6, 2
	s_nop 1
	v_writelane_b32 v245, s7, 3
	s_add_u32 s6, s50, 0x12700000
	s_addc_u32 s7, s51, 0
	v_writelane_b32 v245, s6, 4
	s_add_u32 s5, s50, 0x3df00000
	s_nop 0
	v_writelane_b32 v245, s7, 5
	v_writelane_b32 v245, s5, 6
	s_addc_u32 s5, s51, 0
	s_cmpk_gt_u32 s33, 0xff
	v_writelane_b32 v245, s5, 7
	s_cselect_b64 s[6:7], -1, 0
	s_sub_i32 s5, 11, s39
	s_cmpk_lt_u32 s33, 0x100
	v_writelane_b32 v245, s6, 8
	s_cselect_b64 s[58:59], -1, 0
	s_nop 0
	v_writelane_b32 v245, s7, 9
	s_and_b64 s[6:7], s[58:59], exec
	s_cselect_b32 s5, s39, s5
	s_lshl_b32 s55, s5, 4
	s_ashr_i32 s6, s5, 1
	s_ashr_i32 s60, s55, 31
	s_cmp_gt_u32 s5, 1
	s_cselect_b64 s[10:11], -1, 0
	v_writelane_b32 v245, s10, 10
	s_cmp_lg_u32 s6, 1
	v_writelane_b32 v243, s58, 5
	v_writelane_b32 v245, s11, 11
	s_cselect_b64 s[10:11], -1, 0
	v_writelane_b32 v245, s10, 12
	s_cmp_lg_u32 s6, 2
	v_writelane_b32 v243, s59, 6
	v_writelane_b32 v245, s11, 13
	s_cselect_b64 s[10:11], -1, 0
	v_writelane_b32 v245, s10, 14
	s_cmp_lg_u32 s6, 3
	s_nop 0
	v_writelane_b32 v245, s11, 15
	v_writelane_b32 v245, s6, 16
	v_readlane_b32 s6, v246, 0
	v_readlane_b32 s7, v246, 1
	s_load_dwordx2 s[94:95], s[6:7], 0xa0
	s_cselect_b64 s[10:11], -1, 0
	v_writelane_b32 v245, s10, 17
	s_load_dwordx8 s[20:27], s[6:7], 0x20
	s_waitcnt lgkmcnt(0)
; #define LAS __attribute__((address_space(3)))
; __device__ __forceinline__ unsigned xb_xcc_id() { return (unsigned)__builtin_amdgcn_s_getreg((3 << 11) | 20) & 0xFu; }
; __global__ void __launch_bounds__(NTHR) fwd_megakernel(const Params P) {
;   cg::grid_group grid = cg::this_grid();
;   __shared__ uint4 xb_words;
;   __shared__ int s_vb[4];
;   const int wvi = __builtin_amdgcn_readfirstlane((int)(threadIdx.x >> 6));
;   if (threadIdx.x == 0) xb_words = make_uint4(0u, 0u, 0u, 0u);
;   __syncthreads();
;   (void)xcd_barrier_post((unsigned*)(wsp_plain(P) + OFF_CTL + 65536), (volatile LAS unsigned*)&xb_words, wvi);
;   if (threadIdx.x == 0) {
;     const unsigned x = xb_xcc_id() & 7u;
;     s_vb[1] = (int)x;
;     s_vb[2] = (int)atomicAdd((unsigned*)(P.ws + OFF_CTL + 8192) + x, 1u);
;   }
;   phase0(P, wvi);
;   if (P.ws == nullptr) grid.sync();
;   xcd_barrier(P, (volatile LAS unsigned*)&xb_words, wvi);
;   if (threadIdx.x == 0) {
;     bool even = (gridDim.x & 7u) == 0u;
;     for (int j = 0; j < 8; ++j)
;       even = even && (__hip_atomic_load((unsigned*)(P.ws + OFF_CTL + 8192) + j, __ATOMIC_RELAXED, __HIP_MEMORY_SCOPE_AGENT) == gridDim.x / 8u);
;     s_vb[0] = even ? (s_vb[1] + 8 * s_vb[2]) : (int)blockIdx.x;
;   }
;   __syncthreads();
	s_add_u32 s33, s94, 0x22700000
	s_addc_u32 s92, s95, 0
	v_writelane_b32 v245, s11, 18
	s_add_u32 s5, s94, 0x3500000
	v_writelane_b32 v245, s5, 19
	s_addc_u32 s5, s95, 0
	s_add_u32 s62, s94, 0x2e700000
	s_addc_u32 s63, s95, 0
	s_add_u32 s10, s94, 0x32700000
	v_writelane_b32 v245, s5, 20
	s_addc_u32 s11, s95, 0
	v_writelane_b32 v245, s10, 21
	v_writelane_b32 v243, s62, 7
	s_nop 0
	v_writelane_b32 v245, s11, 22
	s_add_u32 s10, s94, 0x33700000
	s_addc_u32 s11, s95, 0
	v_writelane_b32 v245, s10, 23
	v_writelane_b32 v243, s63, 8
	s_nop 0
	v_writelane_b32 v245, s11, 24
	s_add_u32 s10, s94, 0x16700000
	s_addc_u32 s11, s95, 0
	s_add_u32 s64, s94, 0x12700000
	v_writelane_b32 v245, s10, 25
	s_addc_u32 s65, s95, 0
	s_add_u32 s5, s94, 0x3df10000
	v_writelane_b32 v245, s11, 26
	v_writelane_b32 v245, s5, 27
	s_addc_u32 s5, s95, 0
	s_add_u32 s10, s94, 0x3df10200
	v_writelane_b32 v245, s5, 28
	s_addc_u32 s11, s95, 0
	v_writelane_b32 v245, s10, 29
	s_nop 1
	v_writelane_b32 v245, s11, 30
	s_add_u32 s10, s94, 0x3df10400
	s_addc_u32 s11, s95, 0
	v_writelane_b32 v245, s10, 31
	s_nop 1
	v_writelane_b32 v245, s11, 32
	s_add_u32 s10, s94, 0x3df10500
	s_addc_u32 s11, s95, 0
	v_writelane_b32 v245, s10, 33
	s_nop 1
	v_writelane_b32 v245, s11, 34
	s_add_u32 s10, s94, 0x3df10600
	s_addc_u32 s11, s95, 0
	v_writelane_b32 v245, s10, 35
	s_nop 1
	v_writelane_b32 v245, s11, 36
	s_add_u32 s10, s94, 0x3df10700
	s_addc_u32 s11, s95, 0
	v_writelane_b32 v245, s10, 37
	s_nop 1
	v_writelane_b32 v245, s11, 38
	s_add_u32 s10, s94, 0x3df10800
	s_addc_u32 s11, s95, 0
	v_writelane_b32 v245, s10, 39
	s_nop 1
	v_writelane_b32 v245, s11, 40
	s_add_u32 s10, s94, 0x3df10900
	s_addc_u32 s11, s95, 0
	v_writelane_b32 v245, s10, 41
	s_nop 1
	v_writelane_b32 v245, s11, 42
	s_add_u32 s10, s94, 0x3df10a00
	s_addc_u32 s11, s95, 0
	v_writelane_b32 v245, s10, 43
	s_nop 1
	v_writelane_b32 v245, s11, 44
	s_add_u32 s10, s94, 0x3df10b00
	s_addc_u32 s11, s95, 0
	v_writelane_b32 v245, s10, 45
	s_nop 1
	v_writelane_b32 v245, s11, 46
	s_add_u32 s10, s94, 0x3df10c00
	s_addc_u32 s11, s95, 0
	v_writelane_b32 v245, s10, 47
	s_nop 1
	v_writelane_b32 v245, s11, 48
	s_add_u32 s10, s94, 0x3df10d00
	s_addc_u32 s11, s95, 0
	v_writelane_b32 v245, s10, 49
	s_nop 1
	v_writelane_b32 v245, s11, 50
	s_add_u32 s10, s94, 0x3df10e00
	s_addc_u32 s11, s95, 0
	v_writelane_b32 v245, s10, 51
	s_nop 1
	v_writelane_b32 v245, s11, 52
	s_add_u32 s10, s94, 0x3df10f00
	s_addc_u32 s11, s95, 0
	v_writelane_b32 v245, s10, 53
	s_nop 1
	v_writelane_b32 v245, s11, 54
	s_add_u32 s10, s94, 0x3df11000
	s_addc_u32 s11, s95, 0
	v_writelane_b32 v245, s10, 55
	s_nop 1
	v_writelane_b32 v245, s11, 56
	s_add_u32 s10, s94, 0x3df11100
	s_addc_u32 s11, s95, 0
	v_writelane_b32 v245, s10, 57
	s_nop 1
	v_writelane_b32 v245, s11, 58
	s_add_u32 s10, s94, 0x3df11200
	s_addc_u32 s11, s95, 0
	v_writelane_b32 v245, s10, 59
	s_nop 1
	v_writelane_b32 v245, s11, 60
	s_add_u32 s10, s94, 0x3df11300
	s_addc_u32 s11, s95, 0
	v_writelane_b32 v245, s10, 61
	s_nop 1
	v_writelane_b32 v245, s11, 62
	s_add_u32 s10, s94, 0x3df13400
	s_addc_u32 s11, s95, 0
	v_writelane_b32 v245, s10, 63
	s_nop 1
	v_writelane_b32 v244, s11, 0
	s_add_u32 s10, s94, 0x3df13500
	s_addc_u32 s11, s95, 0
	s_add_u32 s66, s94, 0xa700000
	v_writelane_b32 v244, s10, 1
	s_addc_u32 s67, s95, 0
	v_writelane_b32 v243, s66, 9
	v_writelane_b32 v244, s11, 2
	s_add_u32 s10, s94, 0x35f00000
	s_addc_u32 s11, s95, 0
	v_writelane_b32 v244, s10, 3
	v_writelane_b32 v243, s67, 10
	s_nop 0
	v_writelane_b32 v244, s11, 4
	s_add_u32 s10, s94, 0x26700000
	s_addc_u32 s11, s95, 0
	v_writelane_b32 v244, s10, 5
	s_lshl_b32 s5, s41, 5
	s_nop 0
	v_writelane_b32 v244, s11, 6
	v_writelane_b32 v244, s5, 7
	s_lshl_b32 s5, s42, 5
	s_add_u32 s61, s94, 0x4500000
	s_addc_u32 s68, s95, 0
	s_add_u32 s69, s94, 0x5500000
	s_addc_u32 s70, s95, 0
	s_add_u32 s72, s94, 0x1e700000
	s_addc_u32 s73, s95, 0
	s_add_u32 s71, s94, 0x5d00000
	s_addc_u32 s74, s95, 0
	s_add_u32 s76, s94, 0x1a700000
	s_addc_u32 s77, s95, 0
	s_add_u32 s75, s94, 0x6500000
	v_writelane_b32 v244, s5, 8
	s_addc_u32 s78, s95, 0
	s_or_b32 s5, s54, 16
	v_writelane_b32 v244, s5, 9
	s_or_b32 s5, s54, 0x80
	v_writelane_b32 v244, s5, 10
	s_or_b32 s5, s54, 0x90
	s_add_u32 s79, s94, 0x9100000
	v_writelane_b32 v244, s5, 11
	s_addc_u32 s80, s95, 0
	s_add_i32 s1, s1, 32
	v_writelane_b32 v244, s1, 12
	s_add_i32 s1, s2, 32
	s_add_i32 s0, s0, 32
	v_writelane_b32 v244, s1, 13
	s_add_i32 s1, s3, 32
	v_writelane_b32 v244, s1, 14
	s_add_i32 s1, s4, 32
	s_add_i32 s81, s0, 0x10000
	s_add_i32 s82, s0, 0x14000
	s_add_i32 s83, s0, 0x18000
	s_add_i32 s84, s0, 0x1c000
	s_add_u32 s0, s50, 0x80080
	v_writelane_b32 v244, s1, 15
	s_addc_u32 s1, s51, 0
	v_writelane_b32 v244, s0, 16
	s_load_dwordx2 s[2:3], s[6:7], 0x10
	v_writelane_b32 v243, s61, 11
	v_writelane_b32 v244, s1, 17
	v_writelane_b32 v244, s41, 18
	s_lshl_b32 s0, s41, 7
	v_writelane_b32 v244, s0, 19
	s_mov_b32 s0, s42
	v_writelane_b32 v244, s0, 20
	v_writelane_b32 v243, s68, 12
	v_writelane_b32 v243, s69, 13
	v_writelane_b32 v244, s1, 21
	s_lshl_b32 s0, s42, 7
	v_writelane_b32 v244, s0, 22
	s_add_u32 s0, s94, 0x80080
	s_addc_u32 s1, s95, 0
	v_writelane_b32 v244, s0, 23
	v_writelane_b32 v243, s70, 14
	v_writelane_b32 v243, s72, 15
	v_writelane_b32 v244, s1, 24
	s_add_u32 s0, s94, 0x3580080
	v_writelane_b32 v244, s0, 25
	s_addc_u32 s0, s95, 0
	v_writelane_b32 v244, s0, 26
	s_sub_i32 s0, 32, s48
	s_add_i32 s0, s0, 0x23000
	v_writelane_b32 v244, s0, 27
	v_writelane_b32 v244, s8, 28
	s_sub_i32 s0, 0, s8
	v_writelane_b32 v244, s0, 29
	s_add_u32 s0, s94, 0x4600080
	s_addc_u32 s1, s95, 0
	v_writelane_b32 v244, s0, 30
	s_load_dwordx4 s[8:11], s[6:7], 0x90
	v_writelane_b32 v243, s73, 16
	v_writelane_b32 v244, s1, 31
	s_add_u32 s0, s94, 0x5580080
	s_addc_u32 s1, s95, 0
	v_writelane_b32 v244, s0, 32
	v_writelane_b32 v243, s71, 17
	v_writelane_b32 v243, s74, 18
	v_writelane_b32 v244, s1, 33
	s_add_u32 s0, s94, 0x5d80080
	s_addc_u32 s1, s95, 0
	v_writelane_b32 v244, s0, 34
	v_writelane_b32 v243, s76, 19
	s_nop 0
	v_writelane_b32 v244, s1, 35
	s_add_u32 s0, s94, 0x6580080
	s_addc_u32 s1, s95, 0
	v_writelane_b32 v244, s0, 36
	v_writelane_b32 v243, s77, 20
	v_writelane_b32 v243, s75, 21
	v_writelane_b32 v244, s1, 37
	s_add_u32 s0, s94, 0x9260080
	s_addc_u32 s1, s95, 0
	v_writelane_b32 v244, s0, 38
	v_writelane_b32 v243, s78, 22
	v_writelane_b32 v243, s79, 23
	v_writelane_b32 v244, s1, 39
	s_waitcnt lgkmcnt(0)
; #define LAS __attribute__((address_space(3)))
; __device__ __forceinline__ unsigned xb_xcc_id() { return (unsigned)__builtin_amdgcn_s_getreg((3 << 11) | 20) & 0xFu; }
; __global__ void __launch_bounds__(NTHR) fwd_megakernel(const Params P) {
;   cg::grid_group grid = cg::this_grid();
;   __shared__ uint4 xb_words;
;   __shared__ int s_vb[4];
;   const int wvi = __builtin_amdgcn_readfirstlane((int)(threadIdx.x >> 6));
;   if (threadIdx.x == 0) xb_words = make_uint4(0u, 0u, 0u, 0u);
;   __syncthreads();
;   (void)xcd_barrier_post((unsigned*)(wsp_plain(P) + OFF_CTL + 65536), (volatile LAS unsigned*)&xb_words, wvi);
;   if (threadIdx.x == 0) {
;     const unsigned x = xb_xcc_id() & 7u;
;     s_vb[1] = (int)x;
;     s_vb[2] = (int)atomicAdd((unsigned*)(P.ws + OFF_CTL + 8192) + x, 1u);
;   }
;   phase0(P, wvi);
;   if (P.ws == nullptr) grid.sync();
;   xcd_barrier(P, (volatile LAS unsigned*)&xb_words, wvi);
;   if (threadIdx.x == 0) {
;     bool even = (gridDim.x & 7u) == 0u;
;     for (int j = 0; j < 8; ++j)
;       even = even && (__hip_atomic_load((unsigned*)(P.ws + OFF_CTL + 8192) + j, __ATOMIC_RELAXED, __HIP_MEMORY_SCOPE_AGENT) == gridDim.x / 8u);
;     s_vb[0] = even ? (s_vb[1] + 8 * s_vb[2]) : (int)blockIdx.x;
;   }
;   __syncthreads();
	v_writelane_b32 v244, s2, 40
	v_writelane_b32 v243, s80, 24
	v_writelane_b32 v243, s81, 25
	v_writelane_b32 v244, s3, 41
	s_load_dwordx2 s[2:3], s[6:7], 0x78
	v_writelane_b32 v243, s82, 26
	v_writelane_b32 v243, s83, 27
	v_writelane_b32 v243, s55, 28
	v_writelane_b32 v243, s60, 29
	s_waitcnt lgkmcnt(0)
	v_writelane_b32 v244, s2, 42
	v_writelane_b32 v243, s64, 30
	s_mov_b32 s0, 0
	v_writelane_b32 v244, s3, 43
	v_writelane_b32 v244, s8, 44
	v_writelane_b32 v243, s65, 31
	v_writelane_b32 v243, s84, 32
	v_writelane_b32 v244, s9, 45
	v_writelane_b32 v244, s10, 46
	v_writelane_b32 v244, s11, 47
	s_load_dwordx4 s[8:11], s[6:7], 0x40
	v_writelane_b32 v243, s20, 33
	s_waitcnt lgkmcnt(0)
	v_writelane_b32 v244, s8, 48
	s_nop 1
	v_writelane_b32 v244, s9, 49
	v_writelane_b32 v244, s10, 50
	v_writelane_b32 v244, s11, 51
	s_load_dwordx4 s[8:11], s[6:7], 0x58
	v_writelane_b32 v243, s21, 34
	v_writelane_b32 v243, s22, 35
	v_writelane_b32 v243, s23, 36
	v_writelane_b32 v243, s24, 37
	s_waitcnt lgkmcnt(0)
	v_writelane_b32 v244, s8, 52
	v_writelane_b32 v243, s25, 38
	v_writelane_b32 v243, s26, 39
	v_writelane_b32 v244, s9, 53
	v_writelane_b32 v244, s10, 54
	v_writelane_b32 v244, s11, 55
	v_writelane_b32 v244, s48, 56
	v_writelane_b32 v244, s50, 57
	v_writelane_b32 v243, s27, 40
	s_nop 0
	v_writelane_b32 v244, s51, 58
	v_writelane_b32 v244, s52, 59
	s_nop 1
	v_writelane_b32 v244, s53, 60
	v_writelane_b32 v244, s31, 61
	v_writelane_b32 v244, s49, 62
	v_writelane_b32 v244, s54, 63
	s_branch .LBB0_118

; __device__ __forceinline__ void attn_item(const Params& P, const int pass, const int item, const int wvi) {
;     ...
;   if (tid < 257) fb[tid] = lptr(P.rel_bias)[(int)P.bucket[tid] * 16 + h];
.LBB0_555:
	v_mbcnt_lo_u32_b32 v100, -1, 0
	v_mbcnt_hi_u32_b32 v100, -1, v100
	s_and_b32 s2, s12, 15
	s_waitcnt vmcnt(5)
	v_add_u32_e32 v40, s48, v100
	v_cmp_gt_i32_e32 vcc, s97, v40
	s_and_saveexec_b64 s[0:1], vcc
	s_cbranch_execz .LBB0_557
	v_ashrrev_i32_e32 v41, 31, v40
	s_lshl_b32 s3, s2, 2
	v_lshl_add_u32 v1, v40, 2, 32
	v_add_u32_e32 v1, 0x241fc, v1
	v_readlane_b32 s4, v244, 52
	v_readlane_b32 s5, v244, 53
	v_readlane_b32 s6, v244, 54
	v_readlane_b32 s7, v244, 55
	v_lshl_or_b32 v0, v255, 6, s3
	v_add_u32_e32 v0, 0x23820, v0
	ds_read_b32 v0, v0
	s_waitcnt lgkmcnt(0)
	ds_write_b32 v1, v0

; #define ATT_ISSUE(kt_) do { const int ktn_ = (kt_); ATT_LD(0, pk0, pv0); ATT_LD(1, pk1, pv1); ATT_LD(2, pk2_, pv2); ATT_LD(3, pk3, pv3); } while (0)
; __device__ __forceinline__ void attn_item(const Params& P, const int pass, const int item, const int wvi) {
;   unsigned char* ws = wsp_plain(P);
;   const int tid = tidx(wvi), lane = tid & 63, w = wvi, fr = lane & 15, fq = lane >> 4;
;   const int S = (pass == 0) ? 2048 : 16384, nbs = S >> 7;
;   const int h = item & 15, blk = item >> 4, kvh = h >> 2;
;   const int nb = blk % nbs, seqbase = (blk / nbs) * S;
;   const int qb = blk * 128;
;   constexpr int LDV = 144;
;   constexpr int ATT_SET = 128 * LDP * 2 + 128 * LDV * 2;
;   float* fb = (float*)(smem + 2 * ATT_SET);
;   u16* qbuf = (u16*)(ws + OFF_Q);
;   const u16* kbuf = (const u16*)(ws + OFF_K);
;   const u16* vbuf = (const u16*)(ws + OFF_V);
;   if (tid < 257) fb[tid] = lptr(P.rel_bias)[(int)P.bucket[tid] * 16 + h];
;   bf16x8 qf[4];
; #pragma unroll
;   for (int kk = 0; kk < 4; ++kk) qf[kk] = *(const bf16x8*)(qbuf + (size_t)(qb + w * 16 + fr) * DM + h * 128 + kk * 32 + fq * 8);
;   float mrun = lptr(P.attn_sink)[h], lrun = 1.f;
;   f32x4 oacc[8];
; #pragma unroll
;   for (int i = 0; i < 8; ++i) oacc[i] = f32x4{0.f, 0.f, 0.f, 0.f};
;   const float scale = 0.08838834764831845f;
;   const int qi = w * 16 + fr;
;   const int kt_lo = (nb == 0) ? 1 : 0, kt_hi = (nb == nbs - 1) ? 1 : 2;
;   uint4 pk0, pk1, pk2_, pk3, pv0, pv1, pv2, pv3;
;     ...
;   if (w >= 4) __builtin_amdgcn_s_setprio(1);
;   ATT_ISSUE(kt_lo);
.LBB0_559:
	s_ashr_i32 s0, s0, 4
	s_abs_i32 s3, s0
	v_readlane_b32 s4, v243, 59
	s_mul_hi_u32 s4, s3, s4
	s_mul_i32 s5, s4, s34
	s_sub_i32 s3, s3, s5
	s_ashr_i32 s1, s0, 31
	s_add_i32 s5, s4, 1
	s_sub_i32 s6, s3, s34
	s_cmp_ge_u32 s3, s34
	s_cselect_b32 s4, s5, s4
	s_cselect_b32 s3, s6, s3
	s_add_i32 s5, s4, 1
	s_cmp_ge_u32 s3, s34
	s_cselect_b32 s3, s5, s4
	s_xor_b32 s3, s3, s1
	s_sub_i32 s3, s3, s1
	s_mul_i32 s1, s3, s34
	s_sub_i32 s8, s0, s1
	s_cmp_eq_u32 s8, 0
	v_readlane_b32 s4, v243, 41
	s_cselect_b64 s[0:1], -1, 0
	s_cmp_eq_u32 s8, s4
	v_readlane_b32 s5, v243, 56
	s_cselect_b32 s4, 1, 2
	s_lshl_b32 s5, s3, s5
	s_ashr_i32 s6, s5, 31
	s_add_i32 s7, s8, -1
	s_cmp_lg_u64 s[0:1], 0
	v_cndmask_b32_e64 v49, 0, 1, s[0:1]
	s_addc_u32 s0, s8, -1
	s_ashr_i32 s1, s0, 31
	v_ashrrev_i32_e32 v86, 4, v40
	s_lshl_b64 s[0:1], s[0:1], 7
	v_add_u32_e32 v24, 0x200, v40
	v_add_u32_e32 v32, 0x400, v40
	v_add_u32_e32 v40, 0x600, v40
	s_add_u32 s0, s0, s5
	v_ashrrev_i32_e32 v90, 4, v24
	v_ashrrev_i32_e32 v92, 4, v32
	v_ashrrev_i32_e32 v94, 4, v40
	s_addc_u32 s1, s1, s6
	v_ashrrev_i32_e32 v87, 31, v86
	s_lshl_b32 s2, s2, 6
	v_ashrrev_i32_e32 v91, 31, v90
	v_ashrrev_i32_e32 v93, 31, v92
	v_ashrrev_i32_e32 v95, 31, v94
	v_lshl_add_u64 v[16:17], s[0:1], 0, v[86:87]
	v_readlane_b32 s10, v245, 21
	s_and_b32 s18, s2, 0x300
	v_readlane_b32 s2, v245, 23
	v_lshl_add_u64 v[24:25], s[0:1], 0, v[90:91]
	v_lshl_add_u64 v[32:33], s[0:1], 0, v[92:93]
	v_lshl_add_u64 v[40:41], s[0:1], 0, v[94:95]
	v_lshlrev_b64 v[16:17], 10, v[16:17]
	v_readlane_b32 s11, v245, 22
	v_lshlrev_b32_e32 v20, 3, v100
	v_readlane_b32 s3, v245, 24
	v_lshlrev_b64 v[24:25], 10, v[24:25]
	v_lshlrev_b64 v[32:33], 10, v[32:33]
	v_lshlrev_b64 v[40:41], 10, v[40:41]
	v_lshl_add_u64 v[18:19], s[10:11], 0, v[16:17]
	v_and_b32_e32 v20, 0x78, v20
	v_lshl_add_u64 v[16:17], s[2:3], 0, v[16:17]
	v_lshl_add_u64 v[26:27], s[10:11], 0, v[24:25]
	v_lshl_add_u64 v[24:25], s[2:3], 0, v[24:25]
	v_lshl_add_u64 v[34:35], s[10:11], 0, v[32:33]
	v_lshl_add_u64 v[32:33], s[2:3], 0, v[32:33]
	v_lshl_add_u64 v[42:43], s[10:11], 0, v[40:41]
	v_lshl_add_u64 v[40:41], s[2:3], 0, v[40:41]
	v_lshl_add_u64 v[18:19], v[18:19], 0, s[18:19]
	v_lshlrev_b32_e32 v88, 1, v20
	v_mov_b32_e32 v89, v145
	v_lshl_add_u64 v[16:17], v[16:17], 0, s[18:19]
	v_lshl_add_u64 v[26:27], v[26:27], 0, s[18:19]
	v_lshl_add_u64 v[24:25], v[24:25], 0, s[18:19]
	v_lshl_add_u64 v[34:35], v[34:35], 0, s[18:19]
	v_lshl_add_u64 v[32:33], v[32:33], 0, s[18:19]
	v_lshl_add_u64 v[42:43], v[42:43], 0, s[18:19]
	v_lshl_add_u64 v[40:41], v[40:41], 0, s[18:19]
	v_lshl_add_u64 v[18:19], v[18:19], 0, v[88:89]
	v_lshl_add_u64 v[20:21], v[16:17], 0, v[88:89]
	v_lshl_add_u64 v[26:27], v[26:27], 0, v[88:89]
	v_lshl_add_u64 v[28:29], v[24:25], 0, v[88:89]
	v_lshl_add_u64 v[34:35], v[34:35], 0, v[88:89]
	v_lshl_add_u64 v[36:37], v[32:33], 0, v[88:89]
	v_lshl_add_u64 v[42:43], v[42:43], 0, v[88:89]
	s_waitcnt vmcnt(9)
	v_lshl_add_u64 v[44:45], v[40:41], 0, v[88:89]
	global_load_dwordx4 v[16:19], v[18:19], off
	s_nop 0
	global_load_dwordx4 v[20:23], v[20:21], off
	s_nop 0
	global_load_dwordx4 v[24:27], v[26:27], off
	s_nop 0
	global_load_dwordx4 v[28:31], v[28:29], off
	s_nop 0
	global_load_dwordx4 v[32:35], v[34:35], off
	s_nop 0
	global_load_dwordx4 v[36:39], v[36:37], off
	s_nop 0
	global_load_dwordx4 v[40:43], v[42:43], off
	s_nop 0
	global_load_dwordx4 v[44:47], v[44:45], off
	s_movk_i32 s0, 0x120
	s_movk_i32 s1, 0x110
	v_mul_lo_u32 v102, v86, s0
	v_mul_lo_u32 v104, v90, s0
	v_mul_lo_u32 v106, v92, s0
	v_mul_lo_u32 v108, v94, s0
	s_add_u32 s0, s10, s18
	v_mul_lo_u32 v101, v86, s1
	v_mul_lo_u32 v103, v90, s1
	v_mul_lo_u32 v105, v92, s1
	v_mul_lo_u32 v107, v94, s1
	s_addc_u32 s1, s11, 0
	v_and_b32_e32 v50, 63, v100
	v_lshl_add_u64 v[96:97], s[0:1], 0, v[88:89]
	s_add_u32 s0, s2, s18
	v_bfe_u32 v51, v100, 4, 2
	s_addc_u32 s1, s3, 0
	v_lshlrev_b32_e32 v50, 2, v50
	v_lshl_add_u64 v[98:99], s[0:1], 0, v[88:89]
	v_lshlrev_b32_e32 v89, 2, v51
	v_xor_b32_e32 v109, 64, v50
	v_xor_b32_e32 v110, 0x80, v50
	v_lshrrev_b32_e32 v50, 2, v48
	v_or_b32_e32 v50, v89, v50
	v_mul_u32_u24_e32 v112, 0x120, v50
	v_lshlrev_b32_e32 v50, 7, v49
	v_readlane_b32 s0, v244, 29
	v_readfirstlane_b32 s8, v49
	v_mul_u32_u24_e32 v111, 0x110, v48
	v_add_u32_e32 v50, s0, v50
	v_add_u32_e32 v50, v50, v89
	v_sub_u32_e32 v113, v50, v48
	v_lshlrev_b32_e32 v50, 4, v51
	v_lshl_or_b32 v49, v49, 9, v50
	v_lshlrev_b32_e32 v48, 2, v48
	s_waitcnt vmcnt(16)
	v_lshlrev_b32_e32 v52, 2, v100
	v_sub_u32_e32 v48, v49, v48
	v_readlane_b32 s0, v244, 27
	v_and_b32_e32 v52, 12, v52
	v_mov_b32_e32 v116, 1.0
	v_add_u32_e32 v114, s0, v48
	v_add_u32_e32 v114, 0x11fc, v114
	v_mov_b32_e32 v48, 0
	v_lshlrev_b32_e32 v115, 1, v52
	v_mov_b32_e32 v49, v48
	v_mov_b32_e32 v50, v48
	v_mov_b32_e32 v51, v48
	v_mov_b32_e32 v56, v48
	v_mov_b32_e32 v57, v48
	v_mov_b32_e32 v58, v48
	v_mov_b32_e32 v59, v48
	v_mov_b32_e32 v52, v48
	v_mov_b32_e32 v53, v48
	v_mov_b32_e32 v54, v48
	v_mov_b32_e32 v55, v48
	v_mov_b32_e32 v60, v48
	v_mov_b32_e32 v61, v48
	v_mov_b32_e32 v62, v48
	v_mov_b32_e32 v63, v48
	v_mov_b32_e32 v64, v48
	v_mov_b32_e32 v65, v48
	v_mov_b32_e32 v66, v48
	v_mov_b32_e32 v67, v48
	v_mov_b32_e32 v68, v48
	v_mov_b32_e32 v69, v48
	v_mov_b32_e32 v70, v48
	v_mov_b32_e32 v71, v48
	v_mov_b32_e32 v72, v48
	v_mov_b32_e32 v73, v48
	v_mov_b32_e32 v74, v48
	v_mov_b32_e32 v75, v48
	v_mov_b32_e32 v76, v48
	v_mov_b32_e32 v77, v48
	v_mov_b32_e32 v78, v48
	v_mov_b32_e32 v79, v48
; #define ATT_ISSUE(kt_) do { const int ktn_ = (kt_); ATT_LD(0, pk0, pv0); ATT_LD(1, pk1, pv1); ATT_LD(2, pk2_, pv2); ATT_LD(3, pk3, pv3); } while (0)
; #define ATT_ST(i, RK, RV) do { const int q = tid + NTHR * (i), row = q >> 4, c16 = q & 15; \
;       *(uint4*)(Ks + row * LDP + c16 * 8) = RK; *(uint4*)(Vs + row * LDV + c16 * 8) = RV; } while (0)
; __device__ __forceinline__ void attn_item(const Params& P, const int pass, const int item, const int wvi) {
;     ...
;   for (int kt = kt_lo; kt <= kt_hi; ++kt) {
;     u16* Ks = (u16*)(smem + (kt & 1) * ATT_SET);
;     u16* Vs = Ks + 128 * LDP;
;     ATT_ST(0, pk0, pv0); ATT_ST(1, pk1, pv1); ATT_ST(2, pk2_, pv2); ATT_ST(3, pk3, pv3);
;     __syncthreads();
;     ATT_ISSUE((kt < kt_hi) ? kt + 1 : kt);
;     f32x4 sc[8];
;     float mx = -INFINITY;
; #pragma unroll
;     for (int t8 = 0; t8 < 8; ++t8) {
;       f32x4 a = f32x4{0.f, 0.f, 0.f, 0.f};
; #pragma unroll
;       for (int kk = 0; kk < 4; ++kk) {
;         bf16x8 kf = *(const bf16x8*)(Ks + (t8 * 16 + fr) * LDP + kk * 32 + fq * 8);
;         a = __builtin_amdgcn_mfma_f32_16x16x32_bf16(kf, qf[kk], a, 0, 0, 0);
;       }
; #pragma unroll
;       for (int j = 0; j < 4; ++j) {
;         const int rel = (kt - 1) * 128 + t8 * 16 + fq * 4 + j - qi;
;         const bool ok = (rel >= -128) && (rel <= 128);
;         const int ri = ok ? rel + 128 : 0;
;         const float v = ok ? (a[j] * scale + fb[ri]) : -INFINITY;
;         a[j] = v;
;         mx = fmaxf(mx, v);
;       }
;       sc[t8] = a;
.LBB0_560:
	s_bitcmp1_b32 s8, 0
	s_cselect_b32 s0, 0x11800, 0
	s_add_i32 s9, s0, 32
	s_cmp_ge_u32 s8, s4
	s_mov_b32 s2, s8
	v_add3_u32 v80, s9, v101, v88
	s_cselect_b64 s[0:1], -1, 0
	s_add_i32 s8, s8, 1
	s_waitcnt vmcnt(7)
	ds_write_b128 v80, v[16:19]
	v_add3_u32 v16, s9, v102, v88
	s_cmp_lt_u32 s2, s4
	s_waitcnt vmcnt(6)
	ds_write_b128 v16, v[20:23] offset:34816
	v_add3_u32 v16, s9, v103, v88
	s_cselect_b32 s2, s8, s2
	s_waitcnt vmcnt(5)
	ds_write_b128 v16, v[24:27]
	v_add3_u32 v16, s9, v104, v88
	s_add_i32 s2, s2, s7
	s_waitcnt vmcnt(4)
	ds_write_b128 v16, v[28:31] offset:34816
	v_add3_u32 v16, s9, v105, v88
	s_ashr_i32 s3, s2, 31
	s_waitcnt vmcnt(3)
	ds_write_b128 v16, v[32:35]
	v_add3_u32 v16, s9, v106, v88
	s_lshl_b64 s[2:3], s[2:3], 7
	s_waitcnt vmcnt(2)
	ds_write_b128 v16, v[36:39] offset:34816
	v_add3_u32 v16, s9, v107, v88
	s_add_u32 s2, s2, s5
	s_waitcnt vmcnt(1)
	ds_write_b128 v16, v[40:43]
	v_add3_u32 v16, s9, v108, v88
	s_addc_u32 s3, s3, s6
	s_waitcnt vmcnt(0)
	ds_write_b128 v16, v[44:47] offset:34816
	v_lshl_add_u64 v[16:17], s[2:3], 0, v[86:87]
	v_lshlrev_b64 v[16:17], 10, v[16:17]
	v_add_u32_e32 v28, s9, v144
	v_lshl_add_u64 v[18:19], v[96:97], 0, v[16:17]
	v_lshl_add_u64 v[20:21], v[98:99], 0, v[16:17]
	v_add_u32_e32 v126, v28, v111
	s_waitcnt lgkmcnt(0)
	s_barrier
	ds_read_b32 v210, v114
	ds_read_b32 v211, v114 offset:4
	ds_read_b32 v212, v114 offset:8
	ds_read_b32 v213, v114 offset:12
	global_load_dwordx4 v[16:19], v[18:19], off
	s_nop 0
	global_load_dwordx4 v[20:23], v[20:21], off
	ds_read_b128 v[32:35], v126
	v_lshl_add_u64 v[24:25], s[2:3], 0, v[90:91]
	v_lshlrev_b64 v[24:25], 10, v[24:25]
	v_lshl_add_u64 v[26:27], v[96:97], 0, v[24:25]
	v_lshl_add_u64 v[28:29], v[98:99], 0, v[24:25]
	global_load_dwordx4 v[24:27], v[26:27], off
	s_nop 0
	global_load_dwordx4 v[28:31], v[28:29], off
	ds_read_b128 v[40:43], v126 offset:64
	ds_read_b128 v[80:83], v126 offset:128
	s_waitcnt lgkmcnt(2)
	v_mfma_f32_16x16x32_bf16 v[44:47], v[32:35], v[0:3], 0
	v_lshl_add_u64 v[36:37], s[2:3], 0, v[92:93]
	v_lshl_add_u64 v[118:119], s[2:3], 0, v[94:95]
	v_lshlrev_b64 v[36:37], 10, v[36:37]
	s_waitcnt lgkmcnt(1)
	v_mfma_f32_16x16x32_bf16 v[40:43], v[40:43], v[4:7], v[44:47]
	v_lshlrev_b64 v[118:119], 10, v[118:119]
	v_lshl_add_u64 v[38:39], v[96:97], 0, v[36:37]
	v_lshl_add_u64 v[36:37], v[98:99], 0, v[36:37]
	v_lshl_add_u64 v[44:45], v[96:97], 0, v[118:119]
	v_lshl_add_u64 v[46:47], v[98:99], 0, v[118:119]
	global_load_dwordx4 v[32:35], v[38:39], off
	s_nop 0
	global_load_dwordx4 v[36:39], v[36:37], off
	ds_read_b128 v[118:121], v126 offset:192
	s_waitcnt lgkmcnt(1)
	v_mfma_f32_16x16x32_bf16 v[80:83], v[80:83], v[8:11], v[40:43]
	s_nop 2
	global_load_dwordx4 v[40:43], v[44:45], off
	s_nop 0
	global_load_dwordx4 v[44:47], v[46:47], off
	v_cmp_gt_u32_e32 vcc, s97, v113
	s_waitcnt lgkmcnt(0)
	v_mfma_f32_16x16x32_bf16 v[80:83], v[118:121], v[12:15], v[80:83]
	ds_read_b32 v215, v114 offset:64
	ds_read_b32 v216, v114 offset:68
	ds_read_b32 v217, v114 offset:72
	ds_read_b32 v218, v114 offset:76
	s_nop 3
	v_fmamk_f32 v121, v80, 0x3db504f3, v210
	v_fmamk_f32 v118, v81, 0x3db504f3, v211
	v_fmamk_f32 v124, v82, 0x3db504f3, v212
	v_fmamk_f32 v119, v83, 0x3db504f3, v213
	ds_read_b128 v[80:83], v126 offset:4352
	ds_read_b128 v[176:179], v126 offset:4416
	ds_read_b128 v[180:183], v126 offset:4480
	ds_read_b128 v[190:193], v126 offset:4544
	s_waitcnt lgkmcnt(3)
	v_mfma_f32_16x16x32_bf16 v[80:83], v[80:83], v[0:3], 0
	s_waitcnt lgkmcnt(2)
	v_mfma_f32_16x16x32_bf16 v[80:83], v[176:179], v[4:7], v[80:83]
	s_waitcnt lgkmcnt(1)
	v_mfma_f32_16x16x32_bf16 v[80:83], v[180:183], v[8:11], v[80:83]
	s_waitcnt lgkmcnt(0)
	v_mfma_f32_16x16x32_bf16 v[80:83], v[190:193], v[12:15], v[80:83]
	ds_read_b32 v210, v114 offset:128
	ds_read_b32 v211, v114 offset:132
	ds_read_b32 v212, v114 offset:136
	ds_read_b32 v213, v114 offset:140
	s_nop 3
	v_fmamk_f32 v122, v80, 0x3db504f3, v215
	v_fmamk_f32 v120, v81, 0x3db504f3, v216
	v_fmamk_f32 v125, v82, 0x3db504f3, v217
	v_fmamk_f32 v123, v83, 0x3db504f3, v218
	ds_read_b128 v[80:83], v126 offset:8704
	ds_read_b128 v[176:179], v126 offset:8768
	ds_read_b128 v[180:183], v126 offset:8832
	ds_read_b128 v[190:193], v126 offset:8896
	s_waitcnt lgkmcnt(3)
	v_mfma_f32_16x16x32_bf16 v[80:83], v[80:83], v[0:3], 0
	s_waitcnt lgkmcnt(2)
	v_mfma_f32_16x16x32_bf16 v[80:83], v[176:179], v[4:7], v[80:83]
	s_waitcnt lgkmcnt(1)
	v_mfma_f32_16x16x32_bf16 v[80:83], v[180:183], v[8:11], v[80:83]
	s_waitcnt lgkmcnt(0)
	v_mfma_f32_16x16x32_bf16 v[80:83], v[190:193], v[12:15], v[80:83]
	ds_read_b32 v215, v114 offset:192
	ds_read_b32 v216, v114 offset:196
	ds_read_b32 v217, v114 offset:200
	ds_read_b32 v218, v114 offset:204
	s_nop 3
	v_fmamk_f32 v128, v80, 0x3db504f3, v210
	v_fmamk_f32 v127, v81, 0x3db504f3, v211
	v_fmamk_f32 v130, v82, 0x3db504f3, v212
	v_fmamk_f32 v129, v83, 0x3db504f3, v213
	ds_read_b128 v[80:83], v126 offset:13056
	ds_read_b128 v[176:179], v126 offset:13120
	ds_read_b128 v[180:183], v126 offset:13184
	ds_read_b128 v[190:193], v126 offset:13248
	s_waitcnt lgkmcnt(3)
	v_mfma_f32_16x16x32_bf16 v[80:83], v[80:83], v[0:3], 0
	s_waitcnt lgkmcnt(2)
	v_mfma_f32_16x16x32_bf16 v[80:83], v[176:179], v[4:7], v[80:83]
	s_waitcnt lgkmcnt(1)
	v_mfma_f32_16x16x32_bf16 v[80:83], v[180:183], v[8:11], v[80:83]
	s_waitcnt lgkmcnt(0)
	v_mfma_f32_16x16x32_bf16 v[80:83], v[190:193], v[12:15], v[80:83]
	ds_read_b32 v210, v114 offset:256
	ds_read_b32 v211, v114 offset:260
	ds_read_b32 v212, v114 offset:264
	ds_read_b32 v213, v114 offset:268
	s_nop 3
	v_fmamk_f32 v136, v80, 0x3db504f3, v215
	v_fmamk_f32 v131, v81, 0x3db504f3, v216
	v_fmamk_f32 v138, v82, 0x3db504f3, v217
	v_fmamk_f32 v139, v83, 0x3db504f3, v218
	ds_read_b128 v[80:83], v126 offset:17408
	ds_read_b128 v[176:179], v126 offset:17472
	ds_read_b128 v[180:183], v126 offset:17536
	ds_read_b128 v[190:193], v126 offset:17600
	s_waitcnt lgkmcnt(3)
; __device__ __forceinline__ void attn_item(const Params& P, const int pass, const int item, const int wvi) {
;     ...
;     for (int t8 = 0; t8 < 8; ++t8) {
;       f32x4 a = f32x4{0.f, 0.f, 0.f, 0.f};
; #pragma unroll
;       for (int kk = 0; kk < 4; ++kk) {
;         bf16x8 kf = *(const bf16x8*)(Ks + (t8 * 16 + fr) * LDP + kk * 32 + fq * 8);
;         a = __builtin_amdgcn_mfma_f32_16x16x32_bf16(kf, qf[kk], a, 0, 0, 0);
;       }
; #pragma unroll
;       for (int j = 0; j < 4; ++j) {
;         const int rel = (kt - 1) * 128 + t8 * 16 + fq * 4 + j - qi;
;         const bool ok = (rel >= -128) && (rel <= 128);
;         const int ri = ok ? rel + 128 : 0;
;         const float v = ok ? (a[j] * scale + fb[ri]) : -INFINITY;
;         a[j] = v;
;         mx = fmaxf(mx, v);
;       }
;       sc[t8] = a;
;     }
;     mx = fmaxf(mx, shfl_src(mx, lane ^ 16));
;     mx = fmaxf(mx, shfl_src(mx, lane ^ 32));
;     const float mnew = fmaxf(mrun, mx);
;     const float alpha = __expf(mrun - mnew);
;     float psum = 0.f;
; #pragma unroll
;     for (int t8 = 0; t8 < 8; ++t8)
; #pragma unroll
;       for (int j = 0; j < 4; ++j) { const float pv = __expf(sc[t8][j] - mnew); sc[t8][j] = pv; psum += pv; }
	v_mfma_f32_16x16x32_bf16 v[80:83], v[80:83], v[0:3], 0
	s_waitcnt lgkmcnt(2)
	v_mfma_f32_16x16x32_bf16 v[80:83], v[176:179], v[4:7], v[80:83]
	s_waitcnt lgkmcnt(1)
	v_mfma_f32_16x16x32_bf16 v[80:83], v[180:183], v[8:11], v[80:83]
	s_waitcnt lgkmcnt(0)
	v_mfma_f32_16x16x32_bf16 v[80:83], v[190:193], v[12:15], v[80:83]
	ds_read_b32 v215, v114 offset:320
	ds_read_b32 v216, v114 offset:324
	ds_read_b32 v217, v114 offset:328
	ds_read_b32 v218, v114 offset:332
	s_nop 3
	v_fmamk_f32 v141, v80, 0x3db504f3, v210
	v_fmamk_f32 v140, v81, 0x3db504f3, v211
	v_fmamk_f32 v143, v82, 0x3db504f3, v212
	v_fmamk_f32 v142, v83, 0x3db504f3, v213
	ds_read_b128 v[80:83], v126 offset:21760
	ds_read_b128 v[176:179], v126 offset:21824
	ds_read_b128 v[180:183], v126 offset:21888
	ds_read_b128 v[190:193], v126 offset:21952
	s_waitcnt lgkmcnt(3)
	v_mfma_f32_16x16x32_bf16 v[80:83], v[80:83], v[0:3], 0
	s_waitcnt lgkmcnt(2)
	v_mfma_f32_16x16x32_bf16 v[80:83], v[176:179], v[4:7], v[80:83]
	s_waitcnt lgkmcnt(1)
	v_mfma_f32_16x16x32_bf16 v[80:83], v[180:183], v[8:11], v[80:83]
	s_waitcnt lgkmcnt(0)
	v_mfma_f32_16x16x32_bf16 v[80:83], v[190:193], v[12:15], v[80:83]
	ds_read_b32 v210, v114 offset:384
	ds_read_b32 v211, v114 offset:388
	ds_read_b32 v212, v114 offset:392
	ds_read_b32 v213, v114 offset:396
	s_nop 3
	v_fmamk_f32 v149, v80, 0x3db504f3, v215
	v_fmamk_f32 v148, v81, 0x3db504f3, v216
	v_fmamk_f32 v152, v82, 0x3db504f3, v217
	v_fmamk_f32 v151, v83, 0x3db504f3, v218
	ds_read_b128 v[80:83], v126 offset:26112
	ds_read_b128 v[176:179], v126 offset:26176
	ds_read_b128 v[180:183], v126 offset:26240
	ds_read_b128 v[190:193], v126 offset:26304
	s_waitcnt lgkmcnt(3)
	v_mfma_f32_16x16x32_bf16 v[80:83], v[80:83], v[0:3], 0
	s_waitcnt lgkmcnt(2)
	v_mfma_f32_16x16x32_bf16 v[80:83], v[176:179], v[4:7], v[80:83]
	s_waitcnt lgkmcnt(1)
	v_mfma_f32_16x16x32_bf16 v[80:83], v[180:183], v[8:11], v[80:83]
	s_waitcnt lgkmcnt(0)
	v_mfma_f32_16x16x32_bf16 v[80:83], v[190:193], v[12:15], v[80:83]
	ds_read_b32 v215, v114 offset:448
	ds_read_b32 v216, v114 offset:452
	ds_read_b32 v217, v114 offset:456
	ds_read_b32 v218, v114 offset:460
	s_nop 3
	v_fmamk_f32 v154, v80, 0x3db504f3, v210
	v_fmamk_f32 v153, v81, 0x3db504f3, v211
	v_fmamk_f32 v156, v82, 0x3db504f3, v212
	v_fmamk_f32 v155, v83, 0x3db504f3, v213
	ds_read_b128 v[80:83], v126 offset:30464
	ds_read_b128 v[176:179], v126 offset:30528
	ds_read_b128 v[180:183], v126 offset:30592
	ds_read_b128 v[190:193], v126 offset:30656
	s_waitcnt lgkmcnt(3)
	v_mfma_f32_16x16x32_bf16 v[80:83], v[80:83], v[0:3], 0
	s_waitcnt lgkmcnt(2)
	v_mfma_f32_16x16x32_bf16 v[80:83], v[176:179], v[4:7], v[80:83]
	s_waitcnt lgkmcnt(1)
	v_mfma_f32_16x16x32_bf16 v[80:83], v[180:183], v[8:11], v[80:83]
	s_waitcnt lgkmcnt(0)
	v_mfma_f32_16x16x32_bf16 v[80:83], v[190:193], v[12:15], v[80:83]
	s_nop 3
	s_nop 3
	v_fmamk_f32 v158, v80, 0x3db504f3, v215
	v_fmamk_f32 v157, v81, 0x3db504f3, v216
	v_fmamk_f32 v159, v82, 0x3db504f3, v217
	v_fmamk_f32 v80, v83, 0x3db504f3, v218
	s_mov_b32 s2, 0xff800000
	v_max3_f32 v81, v121, s2, v118
	v_max3_f32 v81, v81, v124, v119
	v_max3_f32 v81, v81, v122, v120
	v_max3_f32 v81, v81, v125, v123
	v_max3_f32 v81, v81, v128, v127
	v_max3_f32 v81, v81, v130, v129
	v_max3_f32 v81, v81, v136, v131
	v_max3_f32 v81, v81, v138, v139
	v_max3_f32 v81, v81, v141, v140
	v_max3_f32 v81, v81, v143, v142
	v_max3_f32 v81, v81, v149, v148
	v_max3_f32 v81, v81, v152, v151
	v_max3_f32 v81, v81, v154, v153
	v_max3_f32 v81, v81, v156, v155
	v_max3_f32 v81, v81, v158, v157
	v_max3_f32 v81, v81, v159, v80
	ds_bpermute_b32 v82, v109, v81
	v_add_u32_e32 v113, 0x80, v113
	v_add_u32_e32 v114, 0x200, v114
	s_andn2_b64 vcc, exec, s[0:1]
	s_waitcnt lgkmcnt(0)
	v_max_f32_e32 v82, v82, v82
	v_max_f32_e32 v81, v81, v82
	ds_bpermute_b32 v82, v110, v81
	s_waitcnt lgkmcnt(0)
	v_max3_f32 v81, v117, v81, v82
	v_sub_f32_e32 v82, v117, v81
	v_sub_f32_e32 v117, v118, v81
	v_mul_f32_e32 v117, 0x3fb8aa3b, v117
	v_exp_f32_e32 v147, v117
	v_sub_f32_e32 v117, v124, v81
	v_mul_f32_e32 v117, 0x3fb8aa3b, v117
	v_exp_f32_e32 v150, v117
	v_sub_f32_e32 v117, v119, v81
	v_mul_f32_e32 v117, 0x3fb8aa3b, v117
	v_exp_f32_e32 v164, v117
	v_sub_f32_e32 v117, v122, v81
	v_mul_f32_e32 v117, 0x3fb8aa3b, v117
	v_exp_f32_e32 v166, v117
	v_sub_f32_e32 v117, v120, v81
	v_mul_f32_e32 v117, 0x3fb8aa3b, v117
	v_exp_f32_e32 v172, v117
	v_sub_f32_e32 v117, v125, v81
	v_mul_f32_e32 v117, 0x3fb8aa3b, v117
	v_exp_f32_e32 v173, v117
	v_sub_f32_e32 v117, v123, v81
	v_mul_f32_e32 v117, 0x3fb8aa3b, v117
	v_exp_f32_e32 v174, v117
	v_sub_f32_e32 v117, v128, v81
	v_mul_f32_e32 v117, 0x3fb8aa3b, v117
	v_exp_f32_e32 v132, v117
	v_sub_f32_e32 v117, v127, v81
	v_mul_f32_e32 v117, 0x3fb8aa3b, v117
	v_exp_f32_e32 v133, v117
	v_sub_f32_e32 v117, v130, v81
	v_mul_f32_e32 v117, 0x3fb8aa3b, v117
	v_exp_f32_e32 v134, v117
	v_sub_f32_e32 v117, v129, v81
	v_sub_f32_e32 v83, v121, v81
	v_mul_f32_e32 v117, 0x3fb8aa3b, v117
	v_mul_f32_e32 v83, 0x3fb8aa3b, v83
	v_exp_f32_e32 v135, v117
	v_sub_f32_e32 v117, v136, v81
	v_exp_f32_e32 v146, v83
	v_mul_f32_e32 v117, 0x3fb8aa3b, v117
	v_exp_f32_e32 v136, v117
	v_sub_f32_e32 v117, v131, v81
	v_mul_f32_e32 v117, 0x3fb8aa3b, v117
	v_exp_f32_e32 v137, v117
	v_sub_f32_e32 v117, v138, v81
	v_add_f32_e32 v83, 0, v146
	v_mul_f32_e32 v117, 0x3fb8aa3b, v117
	v_add_f32_e32 v83, v147, v83
	v_exp_f32_e32 v138, v117
	v_sub_f32_e32 v117, v139, v81
	v_add_f32_e32 v83, v150, v83
	v_mul_f32_e32 v117, 0x3fb8aa3b, v117
	v_add_f32_e32 v83, v164, v83
	v_exp_f32_e32 v139, v117
	v_sub_f32_e32 v117, v141, v81
	v_add_f32_e32 v83, v166, v83
	v_mul_f32_e32 v117, 0x3fb8aa3b, v117
	v_add_f32_e32 v83, v172, v83
; __device__ __forceinline__ void attn_item(const Params& P, const int pass, const int item, const int wvi) {
;     ...
;     const float mnew = fmaxf(mrun, mx);
;     const float alpha = __expf(mrun - mnew);
;     float psum = 0.f;
; #pragma unroll
;     for (int t8 = 0; t8 < 8; ++t8)
; #pragma unroll
;       for (int j = 0; j < 4; ++j) { const float pv = __expf(sc[t8][j] - mnew); sc[t8][j] = pv; psum += pv; }
;     psum += shfl_src(psum, lane ^ 16);
;     psum += shfl_src(psum, lane ^ 32);
;     lrun = lrun * alpha + psum;
;     mrun = mnew;
; #pragma unroll
;     for (int d8 = 0; d8 < 8; ++d8)
; #pragma unroll
;       for (int j = 0; j < 4; ++j) oacc[d8][j] *= alpha;
; #pragma unroll
;     for (int kp = 0; kp < 4; ++kp) {
;       const bf16x8 pf = pack8(sc[2 * kp][0], sc[2 * kp][1], sc[2 * kp][2], sc[2 * kp][3],
;                               sc[2 * kp + 1][0], sc[2 * kp + 1][1], sc[2 * kp + 1][2], sc[2 * kp + 1][3]);
	v_exp_f32_e32 v124, v117
	v_sub_f32_e32 v117, v140, v81
	v_add_f32_e32 v83, v173, v83
	v_mul_f32_e32 v117, 0x3fb8aa3b, v117
	v_add_f32_e32 v83, v174, v83
	v_exp_f32_e32 v125, v117
	v_sub_f32_e32 v117, v143, v81
	v_add_f32_e32 v83, v132, v83
	v_mul_f32_e32 v117, 0x3fb8aa3b, v117
	v_add_f32_e32 v83, v133, v83
	v_exp_f32_e32 v126, v117
	v_sub_f32_e32 v117, v142, v81
	v_add_f32_e32 v83, v134, v83
	v_mul_f32_e32 v117, 0x3fb8aa3b, v117
	v_add_f32_e32 v83, v135, v83
	v_exp_f32_e32 v127, v117
	v_sub_f32_e32 v117, v149, v81
	v_add_f32_e32 v83, v136, v83
	v_mul_f32_e32 v117, 0x3fb8aa3b, v117
	v_add_f32_e32 v83, v137, v83
	v_exp_f32_e32 v128, v117
	v_sub_f32_e32 v117, v148, v81
	v_add_f32_e32 v83, v138, v83
	v_mul_f32_e32 v117, 0x3fb8aa3b, v117
	v_add_f32_e32 v83, v139, v83
	v_exp_f32_e32 v129, v117
	v_sub_f32_e32 v117, v152, v81
	v_add_f32_e32 v83, v124, v83
	v_mul_f32_e32 v117, 0x3fb8aa3b, v117
	v_add_f32_e32 v83, v125, v83
	v_exp_f32_e32 v130, v117
	v_sub_f32_e32 v117, v151, v81
	v_add_f32_e32 v83, v126, v83
	v_mul_f32_e32 v117, 0x3fb8aa3b, v117
	v_add_f32_e32 v83, v127, v83
	v_exp_f32_e32 v131, v117
	v_add_f32_e32 v83, v128, v83
	v_add_f32_e32 v83, v129, v83
	v_add_f32_e32 v83, v130, v83
	v_add_f32_e32 v117, v131, v83
	v_sub_f32_e32 v83, v154, v81
	v_mul_f32_e32 v83, 0x3fb8aa3b, v83
	v_exp_f32_e32 v83, v83
	v_sub_f32_e32 v80, v80, v81
	v_mul_f32_e32 v80, 0x3fb8aa3b, v80
	v_mul_f32_e32 v82, 0x3fb8aa3b, v82
	v_add_f32_e32 v118, v83, v117
	v_sub_f32_e32 v117, v153, v81
	v_mul_f32_e32 v117, 0x3fb8aa3b, v117
	v_exp_f32_e32 v117, v117
	s_nop 0
	v_add_f32_e32 v119, v117, v118
	v_sub_f32_e32 v118, v156, v81
	v_mul_f32_e32 v118, 0x3fb8aa3b, v118
	v_exp_f32_e32 v118, v118
	s_nop 0
	v_add_f32_e32 v120, v118, v119
	v_sub_f32_e32 v119, v155, v81
	v_mul_f32_e32 v119, 0x3fb8aa3b, v119
	v_exp_f32_e32 v119, v119
	s_nop 0
	v_add_f32_e32 v121, v119, v120
	v_sub_f32_e32 v120, v158, v81
	v_mul_f32_e32 v120, 0x3fb8aa3b, v120
	v_exp_f32_e32 v120, v120
	s_nop 0
	v_add_f32_e32 v122, v120, v121
	v_sub_f32_e32 v121, v157, v81
	v_mul_f32_e32 v121, 0x3fb8aa3b, v121
	v_exp_f32_e32 v121, v121
	s_nop 0
	v_add_f32_e32 v123, v121, v122
	v_sub_f32_e32 v122, v159, v81
	v_mul_f32_e32 v122, 0x3fb8aa3b, v122
	v_exp_f32_e32 v122, v122
	s_nop 0
	v_add_f32_e32 v140, v122, v123
	v_exp_f32_e32 v123, v80
	v_exp_f32_e32 v80, v82
	v_add_f32_e32 v140, v123, v140
	ds_bpermute_b32 v82, v109, v140
	v_pk_mul_f32 v[160:161], v[60:61], v[80:81] op_sel_hi:[1,0]
	v_pk_mul_f32 v[162:163], v[62:63], v[80:81] op_sel_hi:[1,0]
	v_pk_mul_f32 v[168:169], v[64:65], v[80:81] op_sel_hi:[1,0]
	v_pk_mul_f32 v[170:171], v[66:67], v[80:81] op_sel_hi:[1,0]
	s_waitcnt lgkmcnt(0)
	v_add_f32_e32 v82, v140, v82
	v_pk_mul_f32 v[140:141], v[48:49], v[80:81] op_sel_hi:[1,0]
	v_pk_mul_f32 v[48:49], v[76:77], v[80:81] op_sel_hi:[1,0]
	v_add3_u32 v77, s9, v115, v112
	ds_read_b64_tr_b16 v[62:63], v77 offset:39424
	ds_read_b64_tr_b16 v[60:61], v77 offset:34816
	ds_read_b64_tr_b16 v[64:65], v77 offset:34848
	ds_read_b64_tr_b16 v[66:67], v77 offset:39456
	ds_bpermute_b32 v148, v110, v82
	v_pk_mul_f32 v[142:143], v[50:51], v[80:81] op_sel_hi:[1,0]
	v_pk_mul_f32 v[152:153], v[56:57], v[80:81] op_sel_hi:[1,0]
	v_pk_mul_f32 v[154:155], v[58:59], v[80:81] op_sel_hi:[1,0]
	v_pk_mul_f32 v[156:157], v[52:53], v[80:81] op_sel_hi:[1,0]
	v_pk_mul_f32 v[158:159], v[54:55], v[80:81] op_sel_hi:[1,0]
	v_cvt_pk_bf16_f32 v52, v146, v147
	v_cvt_pk_bf16_f32 v53, v150, v164
	v_cvt_pk_bf16_f32 v54, v166, v172
	v_cvt_pk_bf16_f32 v55, v173, v174
	v_pk_mul_f32 v[56:57], v[72:73], v[80:81] op_sel_hi:[1,0]
	v_pk_mul_f32 v[58:59], v[74:75], v[80:81] op_sel_hi:[1,0]
	s_waitcnt lgkmcnt(0)
	v_add_f32_e32 v82, v82, v148
	v_mfma_f32_16x16x32_bf16 v[60:63], v[60:63], v[52:55], v[140:143]
	ds_read_b64_tr_b16 v[72:73], v77 offset:34880
	ds_read_b64_tr_b16 v[74:75], v77 offset:39488
	s_nop 0
	ds_read_b64_tr_b16 v[140:141], v77 offset:34912
	ds_read_b64_tr_b16 v[142:143], v77 offset:39520
	ds_read_b64_tr_b16 v[146:147], v77 offset:34944
	ds_read_b64_tr_b16 v[148:149], v77 offset:39552
	v_mfma_f32_16x16x32_bf16 v[64:67], v[64:67], v[52:55], v[152:155]
	ds_read_b64_tr_b16 v[150:151], v77 offset:34976
	s_nop 1
	ds_read_b64_tr_b16 v[152:153], v77 offset:39584
	v_pk_mul_f32 v[68:69], v[68:69], v[80:81] op_sel_hi:[1,0]
	v_pk_mul_f32 v[70:71], v[70:71], v[80:81] op_sel_hi:[1,0]
	v_pk_mul_f32 v[50:51], v[78:79], v[80:81] op_sel_hi:[1,0]
	s_waitcnt lgkmcnt(6)
	v_mfma_f32_16x16x32_bf16 v[72:75], v[72:75], v[52:55], v[156:159]
	v_add_u32_e32 v76, 0x8800, v77
	v_fmac_f32_e32 v82, v116, v80
	s_waitcnt lgkmcnt(0)
	v_mfma_f32_16x16x32_bf16 v[68:71], v[150:153], v[52:55], v[68:71]
	ds_read_b64_tr_b16 v[150:151], v77 offset:35008
	ds_read_b64_tr_b16 v[152:153], v77 offset:39616
	s_waitcnt lgkmcnt(0)
	v_mfma_f32_16x16x32_bf16 v[56:59], v[150:153], v[52:55], v[56:59]
	ds_read_b64_tr_b16 v[150:151], v77 offset:35040
	ds_read_b64_tr_b16 v[152:153], v77 offset:39648
	v_mfma_f32_16x16x32_bf16 v[140:143], v[140:143], v[52:55], v[160:163]
	v_mfma_f32_16x16x32_bf16 v[146:149], v[146:149], v[52:55], v[168:171]
	s_waitcnt lgkmcnt(0)
; __device__ __forceinline__ void attn_item(const Params& P, const int pass, const int item, const int wvi) {
;     ...
; #pragma unroll
;     for (int kp = 0; kp < 4; ++kp) {
;       const bf16x8 pf = pack8(sc[2 * kp][0], sc[2 * kp][1], sc[2 * kp][2], sc[2 * kp][3],
;                               sc[2 * kp + 1][0], sc[2 * kp + 1][1], sc[2 * kp + 1][2], sc[2 * kp + 1][3]);
; #pragma unroll
;       for (int d8 = 0; d8 < 8; ++d8) {
;         const u16* va = Vs + (kp * 32 + fq * 4 + (fr >> 2)) * LDV + d8 * 16 + (fr & 3) * 4;
;         s16x4 v0 = ldtr(va), v1 = ldtr(va + 16 * LDV);
;         oacc[d8] = __builtin_amdgcn_mfma_f32_16x16x32_bf16(cat8(v0, v1), pf, oacc[d8], 0, 0, 0);
;       }
;     }
;   }
	v_mfma_f32_16x16x32_bf16 v[48:51], v[150:153], v[52:55], v[48:51]
	v_cvt_pk_bf16_f32 v52, v132, v133
	v_cvt_pk_bf16_f32 v53, v134, v135
	ds_read_b64_tr_b16 v[132:133], v77 offset:44032
	ds_read_b64_tr_b16 v[134:135], v77 offset:48640
	v_cvt_pk_bf16_f32 v54, v136, v137
	v_cvt_pk_bf16_f32 v55, v138, v139
	s_waitcnt lgkmcnt(0)
	s_nop 0
	v_mfma_f32_16x16x32_bf16 v[60:63], v[132:135], v[52:55], v[60:63]
	ds_read_b64_tr_b16 v[132:133], v77 offset:44064
	ds_read_b64_tr_b16 v[134:135], v77 offset:48672
	s_waitcnt lgkmcnt(0)
	v_mfma_f32_16x16x32_bf16 v[64:67], v[132:135], v[52:55], v[64:67]
	ds_read_b64_tr_b16 v[132:133], v77 offset:44096
	ds_read_b64_tr_b16 v[134:135], v77 offset:48704
	s_waitcnt lgkmcnt(0)
	v_mfma_f32_16x16x32_bf16 v[72:75], v[132:135], v[52:55], v[72:75]
	ds_read_b64_tr_b16 v[132:133], v77 offset:44128
	ds_read_b64_tr_b16 v[134:135], v77 offset:48736
	ds_read_b64_tr_b16 v[136:137], v77 offset:44160
	ds_read_b64_tr_b16 v[138:139], v77 offset:48768
	s_waitcnt lgkmcnt(2)
	v_mfma_f32_16x16x32_bf16 v[132:135], v[132:135], v[52:55], v[140:143]
	s_nop 2
	ds_read_b64_tr_b16 v[140:141], v77 offset:44192
	ds_read_b64_tr_b16 v[142:143], v77 offset:48800
	s_waitcnt lgkmcnt(0)
	v_mfma_f32_16x16x32_bf16 v[68:71], v[140:143], v[52:55], v[68:71]
	ds_read_b64_tr_b16 v[140:141], v77 offset:44224
	ds_read_b64_tr_b16 v[142:143], v77 offset:48832
	s_waitcnt lgkmcnt(0)
	v_mfma_f32_16x16x32_bf16 v[56:59], v[140:143], v[52:55], v[56:59]
	ds_read_b64_tr_b16 v[140:141], v77 offset:44256
	ds_read_b64_tr_b16 v[142:143], v77 offset:48864
	v_mfma_f32_16x16x32_bf16 v[136:139], v[136:139], v[52:55], v[146:149]
	s_waitcnt lgkmcnt(0)
	v_mfma_f32_16x16x32_bf16 v[48:51], v[140:143], v[52:55], v[48:51]
	v_cvt_pk_bf16_f32 v52, v124, v125
	v_cvt_pk_bf16_f32 v53, v126, v127
	ds_read_b64_tr_b16 v[124:125], v77 offset:53248
	ds_read_b64_tr_b16 v[126:127], v77 offset:57856
	v_cvt_pk_bf16_f32 v54, v128, v129
	v_cvt_pk_bf16_f32 v55, v130, v131
	v_cvt_pk_bf16_f32 v140, v83, v117
	v_cvt_pk_bf16_f32 v141, v118, v119
	s_waitcnt lgkmcnt(0)
	v_mfma_f32_16x16x32_bf16 v[60:63], v[124:127], v[52:55], v[60:63]
	ds_read_b64_tr_b16 v[124:125], v77 offset:53280
	ds_read_b64_tr_b16 v[126:127], v77 offset:57888
	v_cvt_pk_bf16_f32 v142, v120, v121
	v_cvt_pk_bf16_f32 v143, v122, v123
	s_waitcnt lgkmcnt(0)
	v_mfma_f32_16x16x32_bf16 v[64:67], v[124:127], v[52:55], v[64:67]
	ds_read_b64_tr_b16 v[124:125], v77 offset:53312
	ds_read_b64_tr_b16 v[126:127], v77 offset:57920
	s_waitcnt lgkmcnt(0)
	v_mfma_f32_16x16x32_bf16 v[72:75], v[124:127], v[52:55], v[72:75]
	ds_read_b64_tr_b16 v[124:125], v77 offset:53344
	ds_read_b64_tr_b16 v[126:127], v77 offset:57952
	ds_read_b64_tr_b16 v[128:129], v77 offset:53376
	ds_read_b64_tr_b16 v[130:131], v77 offset:57984
	s_waitcnt lgkmcnt(2)
	v_mfma_f32_16x16x32_bf16 v[124:127], v[124:127], v[52:55], v[132:135]
	s_nop 2
	ds_read_b64_tr_b16 v[132:133], v77 offset:53408
	ds_read_b64_tr_b16 v[134:135], v77 offset:58016
	s_waitcnt lgkmcnt(0)
	v_mfma_f32_16x16x32_bf16 v[68:71], v[132:135], v[52:55], v[68:71]
	ds_read_b64_tr_b16 v[132:133], v77 offset:53440
	ds_read_b64_tr_b16 v[134:135], v77 offset:58048
	s_waitcnt lgkmcnt(0)
	v_mfma_f32_16x16x32_bf16 v[132:135], v[132:135], v[52:55], v[56:59]
	s_nop 2
	ds_read_b64_tr_b16 v[56:57], v77 offset:53472
	ds_read_b64_tr_b16 v[58:59], v77 offset:58080
	v_mfma_f32_16x16x32_bf16 v[128:131], v[128:131], v[52:55], v[136:139]
	s_waitcnt lgkmcnt(0)
	v_mfma_f32_16x16x32_bf16 v[136:139], v[56:59], v[52:55], v[48:51]
	s_nop 2
	ds_read_b64_tr_b16 v[48:49], v77 offset:62464
	ds_read_b64_tr_b16 v[50:51], v76 offset:32256
	ds_read_b64_tr_b16 v[54:55], v76 offset:32288
	ds_read_b64_tr_b16 v[52:53], v77 offset:62496
	s_waitcnt lgkmcnt(0)
	v_mfma_f32_16x16x32_bf16 v[56:59], v[52:55], v[140:143], v[64:67]
	ds_read_b64_tr_b16 v[52:53], v77 offset:62528
	ds_read_b64_tr_b16 v[54:55], v76 offset:32320
	v_mfma_f32_16x16x32_bf16 v[48:51], v[48:51], v[140:143], v[60:63]
	s_nop 2
	ds_read_b64_tr_b16 v[60:61], v77 offset:62560
	ds_read_b64_tr_b16 v[62:63], v76 offset:32352
	ds_read_b64_tr_b16 v[64:65], v77 offset:62592
	ds_read_b64_tr_b16 v[66:67], v76 offset:32384
	s_waitcnt lgkmcnt(4)
	v_mfma_f32_16x16x32_bf16 v[52:55], v[52:55], v[140:143], v[72:75]
	s_nop 2
	ds_read_b64_tr_b16 v[72:73], v77 offset:62624
	ds_read_b64_tr_b16 v[74:75], v76 offset:32416
	s_waitcnt lgkmcnt(0)
	v_mfma_f32_16x16x32_bf16 v[68:71], v[72:75], v[140:143], v[68:71]
	ds_read_b64_tr_b16 v[72:73], v77 offset:62656
	ds_read_b64_tr_b16 v[74:75], v76 offset:32448
	ds_read_b64_tr_b16 v[118:119], v77 offset:62688
	ds_read_b64_tr_b16 v[120:121], v76 offset:32480
	v_mfma_f32_16x16x32_bf16 v[60:63], v[60:63], v[140:143], v[124:127]
	v_mfma_f32_16x16x32_bf16 v[64:67], v[64:67], v[140:143], v[128:131]
	s_waitcnt lgkmcnt(2)
	v_mfma_f32_16x16x32_bf16 v[72:75], v[72:75], v[140:143], v[132:135]
	s_waitcnt lgkmcnt(0)
	v_mfma_f32_16x16x32_bf16 v[76:79], v[118:121], v[140:143], v[136:139]
	s_cbranch_vccz .LBB0_626
	v_mov_b32_e32 v117, v81
	v_mov_b32_e32 v116, v82
	s_branch .LBB0_560

; __global__ void __launch_bounds__(NTHR) fwd_megakernel(const Params P) {
;   cg::grid_group grid = cg::this_grid();
;   __shared__ uint4 xb_words;
;   __shared__ int s_vb[4];
;   const int wvi = __builtin_amdgcn_readfirstlane((int)(threadIdx.x >> 6));
	.amdhsa_kernel _Z14fwd_megakernel6Params
		.amdhsa_group_segment_fixed_size 4128
		.amdhsa_private_segment_fixed_size 0
		.amdhsa_kernarg_size 688
		.amdhsa_user_sgpr_count 2
		.amdhsa_user_sgpr_dispatch_ptr 0
		.amdhsa_user_sgpr_queue_ptr 0
		.amdhsa_user_sgpr_kernarg_segment_ptr 1
		.amdhsa_user_sgpr_dispatch_id 0
		.amdhsa_user_sgpr_kernarg_preload_length 0
		.amdhsa_user_sgpr_kernarg_preload_offset 0
		.amdhsa_user_sgpr_private_segment_size 0
		.amdhsa_uses_dynamic_stack 0
		.amdhsa_enable_private_segment 0
		.amdhsa_system_sgpr_workgroup_id_x 1
		.amdhsa_system_sgpr_workgroup_id_y 0
		.amdhsa_system_sgpr_workgroup_id_z 0
		.amdhsa_system_sgpr_workgroup_info 0
		.amdhsa_system_vgpr_workitem_id 2
		.amdhsa_next_free_vgpr 256
		.amdhsa_next_free_sgpr 102
		.amdhsa_accum_offset 256
		.amdhsa_reserve_vcc 1
		.amdhsa_float_round_mode_32 0
		.amdhsa_float_round_mode_16_64 0
		.amdhsa_float_denorm_mode_32 3
		.amdhsa_float_denorm_mode_16_64 3
		.amdhsa_dx10_clamp 1
		.amdhsa_ieee_mode 1
		.amdhsa_fp16_overflow 0
		.amdhsa_tg_split 0
		.amdhsa_exception_fp_ieee_invalid_op 0
		.amdhsa_exception_fp_denorm_src 0
		.amdhsa_exception_fp_ieee_div_zero 0
		.amdhsa_exception_fp_ieee_overflow 0
		.amdhsa_exception_fp_ieee_underflow 0
		.amdhsa_exception_fp_ieee_inexact 0
		.amdhsa_exception_int_div_zero 0
	.end_amdhsa_kernel

; __global__ void __launch_bounds__(NTHR) fwd_megakernel(const Params P) {
;   cg::grid_group grid = cg::this_grid();
;   __shared__ uint4 xb_words;
;   __shared__ int s_vb[4];
;   const int wvi = __builtin_amdgcn_readfirstlane((int)(threadIdx.x >> 6));
amdhsa.kernels:
  - .agpr_count:     0
    .args:
      - .offset:         0
        .size:           432
        .value_kind:     by_value
      - .offset:         432
        .size:           4
        .value_kind:     hidden_block_count_x
      - .offset:         436
        .size:           4
        .value_kind:     hidden_block_count_y
      - .offset:         440
        .size:           4
        .value_kind:     hidden_block_count_z
      - .offset:         444
        .size:           2
        .value_kind:     hidden_group_size_x
      - .offset:         446
        .size:           2
        .value_kind:     hidden_group_size_y
      - .offset:         448
        .size:           2
        .value_kind:     hidden_group_size_z
      - .offset:         450
        .size:           2
        .value_kind:     hidden_remainder_x
      - .offset:         452
        .size:           2
        .value_kind:     hidden_remainder_y
      - .offset:         454
        .size:           2
        .value_kind:     hidden_remainder_z
      - .offset:         472
        .size:           8
        .value_kind:     hidden_global_offset_x
      - .offset:         480
        .size:           8
        .value_kind:     hidden_global_offset_y
      - .offset:         488
        .size:           8
        .value_kind:     hidden_global_offset_z
      - .offset:         496
        .size:           2
        .value_kind:     hidden_grid_dims
      - .offset:         520
        .size:           8
        .value_kind:     hidden_multigrid_sync_arg
      - .offset:         552
        .size:           4
        .value_kind:     hidden_dynamic_lds_size
    .group_segment_fixed_size: 4128
    .kernarg_segment_align: 8
    .kernarg_segment_size: 688
    .language:       OpenCL C
    .language_version:
      - 2
      - 0
    .max_flat_workgroup_size: 512
    .name:           _Z14fwd_megakernel6Params
    .private_segment_fixed_size: 0
    .sgpr_count:     108
    .sgpr_spill_count: 284
    .symbol:         _Z14fwd_megakernel6Params.kd
    .uniform_work_group_size: 1
    .uses_dynamic_stack: false
    .vgpr_count:     256
    .vgpr_spill_count: 0
    .wavefront_size: 64
